# MLA tile loop software-pipelined on 32x32x16 MFMA + diff-attention tile loop software-pipelined
# speedup vs baseline: 1.2124x; 1.0046x over previous
; template <int DQK, int DV, int FLAGS, int qp, int kp, int vts, int op> ...
;     ...
;     const int qpos = q0 + 32 * wave + r32, qmin_w = q0 + 32 * wave, qmax_w = qmin_w + 31;
;     f32x16 o[NDB];
; #pragma unroll
;     for (int d = 0; d < NDB; ++d)
; #pragma unroll
;         for (int r = 0; r < 16; ++r) o[d][r] = 0.f;
;     float m = (FLAGS & AF_ROBUST) ? -1e30f : 0.f, l = 0.f;
;     f32x16 negm;
; #pragma unroll
;     for (int r = 0; r < 16; ++r) negm[r] = 0.f;
;     u32x4 kreg[KPT], vreg[VPT];
;     unsigned kgo[KPT], vgo[VPT], klo[KPT], vlo[VPT];
; #pragma unroll
;     for (int i = 0; i < KPT; ++i) { const int c = tid + i * NTHREADS; const int row = c / KC, cc = c % KC; kgo[i] = (unsigned)(row * kp + cc * 8) * 2u; klo[i] = (unsigned)(row * KROW + cc * 16); }
; #pragma unroll
;     for (int i = 0; i < VPT; ++i) { const int c = tid + i * NTHREADS; const int d = c >> 3, cc = c & 7; vgo[i] = (unsigned)(d * vts + cc * 8) * 2u; vlo[i] = (unsigned)(KT_BYTES + d * VROW + cc * 16); }
;     ...
;     ATT_GLOAD((FLAGS & AF_REV) ? kt_hi - 1 : kt_lo); ATT_LSTORE(0);
;     __syncthreads();
;     ...
;             if (FLAGS & AF_ALIBI) { const float ab = -slope2 * (float)nrel - ((FLAGS & AF_ROBUST) ? 0.f : m);
; #pragma unroll
;                 for (int r = 0; r < 16; ++r) { const float c = (float)(16 * (r >> 3) + (r & 7)); p0[r] = __builtin_fmaf(slope2, c, ab); p1[r] = __builtin_fmaf(slope2, c + 32.f, ab); }
;             } else if (FLAGS & AF_ROBUST) {
; #pragma unroll
;                 for (int r = 0; r < 16; ++r) { p0[r] = 0.f; p1[r] = 0.f; }
;             } else { p0 = negm; p1 = negm; }
;             __builtin_amdgcn_sched_barrier(0);
; #pragma unroll
;             for (int c = 0; c < ND0 / 2; ++c) {
;                 if (c + 1 < ND0 / 2) {
; #pragma unroll
;                     for (int i = 0; i < 2; ++i) { kf[(c + 1) & 1][2 * i] = *(const LAS bf16x8*)(kb + (2 * c + 2 + i) * 32); kf[(c + 1) & 1][2 * i + 1] = *(const LAS bf16x8*)(kb + 32 * KROW + (2 * c + 2 + i) * 32); }
;                 }
; #pragma unroll
;                 for (int i = 0; i < 2; ++i) {
;                     p0 = __builtin_amdgcn_mfma_f32_32x32x16_bf16(kf[c & 1][2 * i], qr[2 * c + i], p0, 0, 0, 0);
;                     p1 = __builtin_amdgcn_mfma_f32_32x32x16_bf16(kf[c & 1][2 * i + 1], qr[2 * c + i], p1, 0, 0, 0);
;                 }
;                 __builtin_amdgcn_sched_barrier(0);
;             }
.LBB0_933:
	s_andn2_b64 vcc, exec, s[8:9]
	v_lshlrev_b32_e32 v198, 3, v17
	s_cbranch_vccnz .LBB0_923
	v_and_b32_e32 v18, 31, v15
	v_and_b32_e32 v19, 19, v15
	v_lshlrev_b32_e32 v20, 1, v15
	v_lshrrev_b32_e32 v15, 1, v15
	s_and_b32 s8, s2, 0xffffffe0
	v_readlane_b32 s12, v255, 39
	v_and_b32_e32 v20, 8, v20
	v_and_b32_e32 v15, 4, v15
	v_mov_b32_e32 v17, v1
	s_add_i32 s20, s8, s12
	v_or3_b32 v15, v19, v20, v15
	s_addk_i32 s8, 0xff40
	v_mov_b32_e32 v64, v1
	v_mov_b32_e32 v65, v1
	v_mul_u32_u24_e32 v201, 0x90, v15
	v_mul_u32_u24_e32 v203, 0x90, v18
	v_lshl_add_u64 v[206:207], s[6:7], 0, v[16:17]
	v_add_u32_e32 v15, s8, v18
	v_mov_b32_e32 v66, v1
	v_mov_b32_e32 v67, v1
	v_mov_b32_e32 v68, v1
	v_mov_b32_e32 v69, v1
	v_mov_b32_e32 v70, v1
	v_mov_b32_e32 v71, v1
	v_mov_b32_e32 v72, v1
	v_mov_b32_e32 v73, v1
	v_mov_b32_e32 v74, v1
	v_mov_b32_e32 v75, v1
	v_mov_b32_e32 v76, v1
	v_mov_b32_e32 v77, v1
	v_mov_b32_e32 v78, v1
	v_mov_b32_e32 v79, v1
	v_mov_b64_e32 v[48:49], v[64:65]
	v_mov_b64_e32 v[32:33], v[64:65]
	v_mov_b64_e32 v[16:17], v[64:65]
	v_mov_b32_e32 v197, v1
	s_or_b32 s21, s20, 31
	s_add_i32 s2, s3, 0xff
	s_addk_i32 s3, 0x100
	v_mov_b32_e32 v208, v14
	v_mov_b32_e32 v209, v14
	v_mov_b32_e32 v210, v14
	v_mov_b32_e32 v211, v14
	s_sub_i32 s34, 0xfe, s11
	v_sub_u32_e32 v205, v15, v198
	s_sub_i32 s22, 0x3fff, s10
	s_mov_b32 s23, 0
	s_mov_b64 s[36:37], 0
	v_mov_b32_e32 v222, 0
	v_mov_b64_e32 v[50:51], v[66:67]
	v_mov_b64_e32 v[52:53], v[68:69]
	v_mov_b64_e32 v[54:55], v[70:71]
	v_mov_b64_e32 v[56:57], v[72:73]
	v_mov_b64_e32 v[58:59], v[74:75]
	v_mov_b64_e32 v[60:61], v[76:77]
	v_mov_b64_e32 v[62:63], v[78:79]
	v_mov_b64_e32 v[34:35], v[66:67]
	v_mov_b64_e32 v[36:37], v[68:69]
	v_mov_b64_e32 v[38:39], v[70:71]
	v_mov_b64_e32 v[40:41], v[72:73]
	v_mov_b64_e32 v[42:43], v[74:75]
	v_mov_b64_e32 v[44:45], v[76:77]
	v_mov_b64_e32 v[46:47], v[78:79]
	v_mov_b64_e32 v[18:19], v[66:67]
	v_mov_b64_e32 v[20:21], v[68:69]
	v_mov_b64_e32 v[22:23], v[70:71]
	v_mov_b64_e32 v[24:25], v[72:73]
	v_mov_b64_e32 v[26:27], v[74:75]
	v_mov_b64_e32 v[28:29], v[76:77]
	v_mov_b64_e32 v[30:31], v[78:79]
	v_mov_b32_e32 v199, 0
	v_readlane_b32 s13, v255, 40
	s_andn2_b64 vcc, exec, s[40:41]
	s_cbranch_vccnz .Ld_fallback
	s_ashr_i32 s35, s34, 31
	s_lshl_b64 s[6:7], s[34:35], 17
	s_lshl_b64 s[10:11], s[34:35], 7
	s_add_u32 s10, s18, s10
	s_addc_u32 s11, s19, s11
	v_lshl_add_u64 v[246:247], v[206:207], 0, s[6:7]
	global_load_dwordx4 v[148:151], v[246:247], off
	v_lshl_add_u64 v[246:247], s[10:11], 0, v[0:1]
	global_load_dwordx4 v[152:155], v[246:247], off
	v_lshl_add_u64 v[246:247], s[10:11], 0, v[196:197]
	global_load_dwordx4 v[156:159], v[246:247], off
	s_add_i32 s34, s34, -1
	s_movk_i32 s13, 0x6c00
	s_waitcnt vmcnt(0)
	v_add_u32_e32 v248, s13, v204
	v_add_u32_e32 v249, s13, v200
	v_add_u32_e32 v250, s13, v202
	ds_write_b128 v248, v[148:151]
	ds_write_b128 v249, v[152:155] offset:9216
	ds_write_b128 v250, v[156:159] offset:9216
	s_ashr_i32 s35, s34, 31
	s_lshl_b64 s[6:7], s[34:35], 17
	s_lshl_b64 s[10:11], s[34:35], 7
	s_add_u32 s10, s18, s10
	s_addc_u32 s11, s19, s11
	v_lshl_add_u64 v[246:247], v[206:207], 0, s[6:7]
	global_load_dwordx4 v[148:151], v[246:247], off
	v_lshl_add_u64 v[246:247], s[10:11], 0, v[0:1]
	global_load_dwordx4 v[152:155], v[246:247], off
	v_lshl_add_u64 v[246:247], s[10:11], 0, v[196:197]
	global_load_dwordx4 v[156:159], v[246:247], off
	s_add_i32 s34, s34, -1
	s_mov_b32 s8, 0x42000000
	s_mov_b32 s9, 0x42040000
	s_sub_i32 s24, s22, s21
	s_ashr_i32 s24, s24, 6
	s_max_i32 s24, s24, 0
	s_waitcnt lgkmcnt(0)
	s_barrier
	s_cmp_lg_u32 s24, 0
	s_cbranch_scc1 .Ld_noqk0
	v_add_u32_e32 v244, v201, v194
	ds_read_b128 v[160:163], v244 offset:0
	ds_read_b128 v[164:167], v244 offset:32
	ds_read_b128 v[168:171], v244 offset:64
	ds_read_b128 v[172:175], v244 offset:96
	ds_read_b128 v[224:227], v244 offset:4608
	ds_read_b128 v[228:231], v244 offset:4640
	ds_read_b128 v[232:235], v244 offset:4672
	ds_read_b128 v[236:239], v244 offset:4704
	v_cvt_f32_i32_e32 v246, v205
	v_fma_f32 v242, -v14, v246, -v222
	v_mov_b32_e32 v80, v242
	v_add_f32_e32 v81, v14, v242
	v_pk_fma_f32 v[82:83], v[208:209], s[62:63], v[242:243] op_sel_hi:[1,1,0]
	v_pk_fma_f32 v[84:85], v[208:209], s[64:65], v[242:243] op_sel_hi:[1,1,0]
	v_pk_fma_f32 v[86:87], v[208:209], s[66:67], v[242:243] op_sel_hi:[1,1,0]
	v_pk_fma_f32 v[88:89], v[208:209], s[68:69], v[242:243] op_sel_hi:[1,1,0]
	v_pk_fma_f32 v[90:91], v[208:209], s[70:71], v[242:243] op_sel_hi:[1,1,0]
	v_pk_fma_f32 v[92:93], v[208:209], s[72:73], v[242:243] op_sel_hi:[1,1,0]
	v_pk_fma_f32 v[94:95], v[208:209], s[76:77], v[242:243] op_sel_hi:[1,1,0]
	v_pk_fma_f32 v[96:97], v[208:209], s[8:9], v[242:243] op_sel_hi:[1,1,0]
	v_pk_fma_f32 v[98:99], v[208:209], s[96:97], v[242:243] op_sel_hi:[1,1,0]
	v_pk_fma_f32 v[100:101], v[208:209], s[94:95], v[242:243] op_sel_hi:[1,1,0]
	v_pk_fma_f32 v[102:103], v[208:209], s[92:93], v[242:243] op_sel_hi:[1,1,0]
	v_pk_fma_f32 v[104:105], v[208:209], s[90:91], v[242:243] op_sel_hi:[1,1,0]
	v_pk_fma_f32 v[106:107], v[208:209], s[88:89], v[242:243] op_sel_hi:[1,1,0]
	v_pk_fma_f32 v[108:109], v[208:209], s[86:87], v[242:243] op_sel_hi:[1,1,0]
	v_pk_fma_f32 v[110:111], v[208:209], s[78:79], v[242:243] op_sel_hi:[1,1,0]
	s_waitcnt lgkmcnt(0)
	v_mfma_f32_32x32x16_bf16 v[80:95], v[160:163], v[2:5], v[80:95]
	v_mfma_f32_32x32x16_bf16 v[96:111], v[224:227], v[2:5], v[96:111]
	v_mfma_f32_32x32x16_bf16 v[80:95], v[164:167], v[6:9], v[80:95]
	v_mfma_f32_32x32x16_bf16 v[96:111], v[228:231], v[6:9], v[96:111]
	v_mfma_f32_32x32x16_bf16 v[80:95], v[168:171], v[10:13], v[80:95]
	v_mfma_f32_32x32x16_bf16 v[96:111], v[232:235], v[10:13], v[96:111]
	v_mfma_f32_32x32x16_bf16 v[80:95], v[172:175], v[144:147], v[80:95]
	v_mfma_f32_32x32x16_bf16 v[96:111], v[236:239], v[144:147], v[96:111]
; #define LAS __attribute__((address_space(3)))
; template <int DQK, int DV, int FLAGS, int qp, int kp, int vts, int op> ...
;     ...
;             if (FLAGS & AF_ALIBI) { const float ab = -slope2 * (float)nrel - ((FLAGS & AF_ROBUST) ? 0.f : m);
; #pragma unroll
;                 for (int r = 0; r < 16; ++r) { const float c = (float)(16 * (r >> 3) + (r & 7)); p0[r] = __builtin_fmaf(slope2, c, ab); p1[r] = __builtin_fmaf(slope2, c + 32.f, ab); }
;             } else if (FLAGS & AF_ROBUST) {
; #pragma unroll
;                 for (int r = 0; r < 16; ++r) { p0[r] = 0.f; p1[r] = 0.f; }
;             } else { p0 = negm; p1 = negm; }
;             __builtin_amdgcn_sched_barrier(0);
; #pragma unroll
;             for (int c = 0; c < ND0 / 2; ++c) {
;                 if (c + 1 < ND0 / 2) {
; #pragma unroll
;                     for (int i = 0; i < 2; ++i) { kf[(c + 1) & 1][2 * i] = *(const LAS bf16x8*)(kb + (2 * c + 2 + i) * 32); kf[(c + 1) & 1][2 * i + 1] = *(const LAS bf16x8*)(kb + 32 * KROW + (2 * c + 2 + i) * 32); }
;                 }
; #pragma unroll
;                 for (int i = 0; i < 2; ++i) {
;                     p0 = __builtin_amdgcn_mfma_f32_32x32x16_bf16(kf[c & 1][2 * i], qr[2 * c + i], p0, 0, 0, 0);
;                     p1 = __builtin_amdgcn_mfma_f32_32x32x16_bf16(kf[c & 1][2 * i + 1], qr[2 * c + i], p1, 0, 0, 0);
;                 }
;                 __builtin_amdgcn_sched_barrier(0);
;             }
;     ...
;             f32x2 rs2 = {0.f, 0.f};
; #pragma unroll
;             for (int r = 0; r < 16; ++r) { p0[r] = __builtin_amdgcn_exp2f(p0[r]); p1[r] = __builtin_amdgcn_exp2f(p1[r]); }
; #pragma unroll
;             for (int r = 0; r < 16; r += 2) { rs2 += (f32x2){p0[r], p0[r + 1]}; rs2 += (f32x2){p1[r], p1[r + 1]}; }
;             l += rs2.x + rs2.y;
;             bf16x8 pf[4];
;             pf[0] = pack_bf16x8(p0, 0); pf[1] = pack_bf16x8(p0, 8); pf[2] = pack_bf16x8(p1, 0); pf[3] = pack_bf16x8(p1, 8);
;             __builtin_amdgcn_sched_barrier(0);
; #pragma unroll
;             for (int d = 0; d < NDB; ++d) {
;                 if (d + 1 < NDB) {
; #pragma unroll
;                     for (int ks = 0; ks < 4; ++ks) vf[(d + 1) & 1][ks] = *(const LAS bf16x8*)(vb + (d + 1) * 32 * VROW + ks * 32);
;                 }
; #pragma unroll
;                 for (int ks = 0; ks < 4; ++ks) o[d] = __builtin_amdgcn_mfma_f32_32x32x16_bf16(vf[d & 1][ks], pf[ks], o[d], 0, 0, 0);
.Ld_noqk0:
.Ld_top0:
	s_cmp_le_i32 s23, s24
	s_cbranch_scc1 .Ld_gen0
	s_add_i32 s13, s23, 1
	s_cmp_ge_i32 s13, s3
	s_cbranch_scc1 .Ld_gen0
	s_add_i32 s12, s23, -1
	s_and_b32 s12, s12, 3
	s_mulk_i32 s12, 0x6c00
	v_add3_u32 v245, s12, v203, v194
	ds_read_b128 v[224:227], v245 offset:13824
	ds_read_b128 v[228:231], v245 offset:13856
	ds_read_b128 v[232:235], v245 offset:13888
	ds_read_b128 v[236:239], v245 offset:13920
	s_add_i32 s12, s23, 1
	s_and_b32 s12, s12, 3
	s_mulk_i32 s12, 0x6c00
	v_add3_u32 v244, s12, v201, v194
	s_and_b32 s12, s23, 3
	s_mulk_i32 s12, 0x6c00
	v_add3_u32 v251, s12, v203, v194
	v_mfma_f32_32x32x16_bf16 v[64:79], v[160:163], v[112:115], v[64:79]
	v_mfma_f32_32x32x16_bf16 v[64:79], v[164:167], v[116:119], v[64:79]
	v_mfma_f32_32x32x16_bf16 v[64:79], v[168:171], v[120:123], v[64:79]
	v_mfma_f32_32x32x16_bf16 v[64:79], v[172:175], v[124:127], v[64:79]
	ds_read_b128 v[160:163], v245 offset:18432
	ds_read_b128 v[164:167], v245 offset:18464
	ds_read_b128 v[168:171], v245 offset:18496
	ds_read_b128 v[172:175], v245 offset:18528
	v_exp_f32_e32 v80, v80
	v_exp_f32_e32 v81, v81
	v_exp_f32_e32 v96, v96
	v_exp_f32_e32 v97, v97
	v_pk_add_f32 v[240:241], v[80:81], 0 op_sel_hi:[1,0]
	v_exp_f32_e32 v82, v82
	v_exp_f32_e32 v83, v83
	v_pk_add_f32 v[240:241], v[96:97], v[240:241]
	v_exp_f32_e32 v98, v98
	v_exp_f32_e32 v99, v99
	v_pk_add_f32 v[240:241], v[82:83], v[240:241]
	s_waitcnt lgkmcnt(4)
	v_mfma_f32_32x32x16_bf16 v[48:63], v[224:227], v[112:115], v[48:63]
	v_mfma_f32_32x32x16_bf16 v[48:63], v[228:231], v[116:119], v[48:63]
	v_mfma_f32_32x32x16_bf16 v[48:63], v[232:235], v[120:123], v[48:63]
	v_mfma_f32_32x32x16_bf16 v[48:63], v[236:239], v[124:127], v[48:63]
	ds_read_b128 v[224:227], v245 offset:23040
	ds_read_b128 v[228:231], v245 offset:23072
	ds_read_b128 v[232:235], v245 offset:23104
	ds_read_b128 v[236:239], v245 offset:23136
	v_exp_f32_e32 v84, v84
	v_exp_f32_e32 v85, v85
	v_pk_add_f32 v[240:241], v[98:99], v[240:241]
	v_exp_f32_e32 v100, v100
	v_exp_f32_e32 v101, v101
	v_pk_add_f32 v[240:241], v[84:85], v[240:241]
	v_exp_f32_e32 v86, v86
	v_exp_f32_e32 v87, v87
	v_pk_add_f32 v[240:241], v[100:101], v[240:241]
	v_exp_f32_e32 v102, v102
	v_exp_f32_e32 v103, v103
	v_pk_add_f32 v[240:241], v[86:87], v[240:241]
	s_waitcnt lgkmcnt(4)
	v_mfma_f32_32x32x16_bf16 v[32:47], v[160:163], v[112:115], v[32:47]
	v_mfma_f32_32x32x16_bf16 v[32:47], v[164:167], v[116:119], v[32:47]
	v_mfma_f32_32x32x16_bf16 v[32:47], v[168:171], v[120:123], v[32:47]
	v_mfma_f32_32x32x16_bf16 v[32:47], v[172:175], v[124:127], v[32:47]
	ds_read_b128 v[160:163], v244 offset:0
	ds_read_b128 v[164:167], v244 offset:32
	ds_read_b128 v[168:171], v244 offset:64
	ds_read_b128 v[172:175], v244 offset:96
	v_exp_f32_e32 v88, v88
	v_exp_f32_e32 v89, v89
	v_pk_add_f32 v[240:241], v[102:103], v[240:241]
	v_exp_f32_e32 v104, v104
	v_exp_f32_e32 v105, v105
	v_pk_add_f32 v[240:241], v[88:89], v[240:241]
	v_exp_f32_e32 v90, v90
	v_exp_f32_e32 v91, v91
	v_pk_add_f32 v[240:241], v[104:105], v[240:241]
	v_exp_f32_e32 v106, v106
	v_exp_f32_e32 v107, v107
	v_pk_add_f32 v[240:241], v[90:91], v[240:241]
	s_waitcnt lgkmcnt(4)
	v_mfma_f32_32x32x16_bf16 v[16:31], v[224:227], v[112:115], v[16:31]
	v_mfma_f32_32x32x16_bf16 v[16:31], v[228:231], v[116:119], v[16:31]
	v_mfma_f32_32x32x16_bf16 v[16:31], v[232:235], v[120:123], v[16:31]
	v_mfma_f32_32x32x16_bf16 v[16:31], v[236:239], v[124:127], v[16:31]
	ds_read_b128 v[224:227], v244 offset:4608
	ds_read_b128 v[228:231], v244 offset:4640
	ds_read_b128 v[232:235], v244 offset:4672
	ds_read_b128 v[236:239], v244 offset:4704
	v_add_u32_e32 v246, 64, v205
	v_cvt_f32_i32_e32 v246, v246
	v_fma_f32 v242, -v14, v246, -v222
	v_mov_b32_e32 v112, v242
	v_add_f32_e32 v113, v14, v242
	v_pk_fma_f32 v[114:115], v[208:209], s[62:63], v[242:243] op_sel_hi:[1,1,0]
	v_pk_fma_f32 v[116:117], v[208:209], s[64:65], v[242:243] op_sel_hi:[1,1,0]
	v_pk_fma_f32 v[118:119], v[208:209], s[66:67], v[242:243] op_sel_hi:[1,1,0]
	v_pk_fma_f32 v[120:121], v[208:209], s[68:69], v[242:243] op_sel_hi:[1,1,0]
	v_pk_fma_f32 v[122:123], v[208:209], s[70:71], v[242:243] op_sel_hi:[1,1,0]
	v_pk_fma_f32 v[124:125], v[208:209], s[72:73], v[242:243] op_sel_hi:[1,1,0]
	v_pk_fma_f32 v[126:127], v[208:209], s[76:77], v[242:243] op_sel_hi:[1,1,0]
	v_pk_fma_f32 v[128:129], v[208:209], s[8:9], v[242:243] op_sel_hi:[1,1,0]
	v_pk_fma_f32 v[130:131], v[208:209], s[96:97], v[242:243] op_sel_hi:[1,1,0]
	v_pk_fma_f32 v[132:133], v[208:209], s[94:95], v[242:243] op_sel_hi:[1,1,0]
	v_pk_fma_f32 v[134:135], v[208:209], s[92:93], v[242:243] op_sel_hi:[1,1,0]
	v_pk_fma_f32 v[136:137], v[208:209], s[90:91], v[242:243] op_sel_hi:[1,1,0]
	v_pk_fma_f32 v[138:139], v[208:209], s[88:89], v[242:243] op_sel_hi:[1,1,0]
	v_pk_fma_f32 v[140:141], v[208:209], s[86:87], v[242:243] op_sel_hi:[1,1,0]
	v_pk_fma_f32 v[142:143], v[208:209], s[78:79], v[242:243] op_sel_hi:[1,1,0]
	v_exp_f32_e32 v92, v92
	v_exp_f32_e32 v93, v93
	v_pk_add_f32 v[240:241], v[106:107], v[240:241]
	v_exp_f32_e32 v108, v108
	v_exp_f32_e32 v109, v109
	v_pk_add_f32 v[240:241], v[92:93], v[240:241]
	v_exp_f32_e32 v94, v94
	v_exp_f32_e32 v95, v95
	v_pk_add_f32 v[240:241], v[108:109], v[240:241]
	v_exp_f32_e32 v110, v110
	v_exp_f32_e32 v111, v111
	v_pk_add_f32 v[240:241], v[94:95], v[240:241]
	s_waitcnt lgkmcnt(4)
	v_mfma_f32_32x32x16_bf16 v[112:127], v[160:163], v[2:5], v[112:127]
	v_mfma_f32_32x32x16_bf16 v[112:127], v[164:167], v[6:9], v[112:127]
	v_mfma_f32_32x32x16_bf16 v[112:127], v[168:171], v[10:13], v[112:127]
	v_mfma_f32_32x32x16_bf16 v[112:127], v[172:175], v[144:147], v[112:127]
	ds_read_b128 v[160:163], v251 offset:9216
	ds_read_b128 v[164:167], v251 offset:9248
	ds_read_b128 v[168:171], v251 offset:9280
	ds_read_b128 v[172:175], v251 offset:9312
	s_nop 0
	v_pk_add_f32 v[240:241], v[110:111], v[240:241]
	v_cvt_pk_bf16_f32 v80, v80, v81
	v_cvt_pk_bf16_f32 v81, v82, v83
	v_cvt_pk_bf16_f32 v82, v84, v85
	v_cvt_pk_bf16_f32 v83, v86, v87
	v_cvt_pk_bf16_f32 v84, v88, v89
	v_cvt_pk_bf16_f32 v85, v90, v91
	v_cvt_pk_bf16_f32 v86, v92, v93
	v_cvt_pk_bf16_f32 v87, v94, v95
	s_waitcnt lgkmcnt(4)
	v_mfma_f32_32x32x16_bf16 v[128:143], v[224:227], v[2:5], v[128:143]
	v_mfma_f32_32x32x16_bf16 v[128:143], v[228:231], v[6:9], v[128:143]
	v_mfma_f32_32x32x16_bf16 v[128:143], v[232:235], v[10:13], v[128:143]
	v_mfma_f32_32x32x16_bf16 v[128:143], v[236:239], v[144:147], v[128:143]
	v_cvt_pk_bf16_f32 v88, v96, v97
	v_cvt_pk_bf16_f32 v89, v98, v99
	v_cvt_pk_bf16_f32 v90, v100, v101
	v_cvt_pk_bf16_f32 v91, v102, v103
	v_cvt_pk_bf16_f32 v92, v104, v105
	v_cvt_pk_bf16_f32 v93, v106, v107
	v_cvt_pk_bf16_f32 v94, v108, v109
	v_cvt_pk_bf16_f32 v95, v110, v111
	v_add_f32_e32 v247, v240, v241
	v_add_f32_e32 v199, v199, v247
	s_branch .Ld_tail0
; template <int DQK, int DV, int FLAGS, int qp, int kp, int vts, int op> ...
;     ...
;             bool need_mask = false;
;             if (FLAGS & AF_CAUSAL) need_mask = need_mask || (kv0 + 63 > qmin_w);
;             if (FLAGS & AF_WINDOW) need_mask = need_mask || (kv0 < qmax_w - (SWA_W - 1));
;             if (need_mask) {
; #pragma unroll
;                 for (int r = 0; r < 16; ++r) { const int c = 16 * (r >> 3) + (r & 7);
;                     bool m0 = false, m1 = false;
;                     if (FLAGS & AF_CAUSAL) { m0 = m0 || (c > nrel); m1 = m1 || (c + 32 > nrel); }
;                     if (FLAGS & AF_WINDOW) { m0 = m0 || (c <= nrel - SWA_W); m1 = m1 || (c + 32 <= nrel - SWA_W); }
;                     if (m0) p0[r] = -INFINITY; if (m1) p1[r] = -INFINITY; }
;             }
;             float mx = 0.f;
;             if ((FLAGS & AF_ROBUST) || !started || !skipmax) {
;               float a = MX3(p0[0], p0[1], p1[0]), b = MX3(p0[2], p0[3], p1[1]); a = MX3(a, p1[2], p1[3]);
; #pragma unroll
;               for (int r = 4; r < 16; r += 4) { a = MX3(a, p0[r], p0[r + 1]); b = MX3(b, p0[r + 2], p0[r + 3]); a = MX3(a, p1[r], p1[r + 1]); b = MX3(b, p1[r + 2], p1[r + 3]); }
;               mx = __builtin_fmaxf(a, b);
;               if ((FLAGS & AF_ROBUST) || !started) mx = __builtin_fmaxf(mx, shfl_xor_l(mx, 32, lane)); }
;             if (FLAGS & AF_ROBUST) {
;                 if (__any(mx > m + 8.0f)) {
;                     const float mn = fmaxf(m, mx), alpha = __builtin_amdgcn_exp2f(m - mn);
;                     l *= alpha; m = mn;
; #pragma unroll
;                     for (int d = 0; d < NDB; ++d)
; #pragma unroll
;                         for (int r = 0; r < 16; ++r) o[d][r] *= alpha;
;                 }
; #pragma unroll
;                 for (int r = 0; r < 16; ++r) { p0[r] -= m; p1[r] -= m; }
;             } else {
;                 if (!started) {
;                     started = true;
;                     m = mx;
; #pragma unroll
;                     for (int r = 0; r < 16; ++r) { p0[r] -= mx; p1[r] -= mx; }
;                     if (!(FLAGS & AF_ALIBI)) {
; #pragma unroll
;                         for (int r = 0; r < 16; ++r) negm[r] = -m;
;                     }
;     ...
;             __builtin_amdgcn_sched_barrier(0);
; #pragma unroll
;             for (int d = 0; d < NDB; ++d) {
;                 if (d + 1 < NDB) {
; #pragma unroll
.Ld_gen0:
	s_cmp_le_i32 s23, s24
	s_cbranch_scc1 .Ld_nopv_p0
	s_waitcnt lgkmcnt(0)
	s_add_i32 s12, s23, -1
	s_and_b32 s12, s12, 3
	s_mulk_i32 s12, 0x6c00
	v_add3_u32 v245, s12, v203, v194
	ds_read_b128 v[224:227], v245 offset:13824
	ds_read_b128 v[228:231], v245 offset:13856
	ds_read_b128 v[232:235], v245 offset:13888
	ds_read_b128 v[236:239], v245 offset:13920
	v_mfma_f32_32x32x16_bf16 v[64:79], v[160:163], v[112:115], v[64:79]
	v_mfma_f32_32x32x16_bf16 v[64:79], v[164:167], v[116:119], v[64:79]
	v_mfma_f32_32x32x16_bf16 v[64:79], v[168:171], v[120:123], v[64:79]
	v_mfma_f32_32x32x16_bf16 v[64:79], v[172:175], v[124:127], v[64:79]
	ds_read_b128 v[160:163], v245 offset:18432
	ds_read_b128 v[164:167], v245 offset:18464
	ds_read_b128 v[168:171], v245 offset:18496
	ds_read_b128 v[172:175], v245 offset:18528
	s_waitcnt lgkmcnt(4)
	v_mfma_f32_32x32x16_bf16 v[48:63], v[224:227], v[112:115], v[48:63]
	v_mfma_f32_32x32x16_bf16 v[48:63], v[228:231], v[116:119], v[48:63]
	v_mfma_f32_32x32x16_bf16 v[48:63], v[232:235], v[120:123], v[48:63]
	v_mfma_f32_32x32x16_bf16 v[48:63], v[236:239], v[124:127], v[48:63]
	ds_read_b128 v[224:227], v245 offset:23040
	ds_read_b128 v[228:231], v245 offset:23072
	ds_read_b128 v[232:235], v245 offset:23104
	ds_read_b128 v[236:239], v245 offset:23136
	s_waitcnt lgkmcnt(4)
	v_mfma_f32_32x32x16_bf16 v[32:47], v[160:163], v[112:115], v[32:47]
	v_mfma_f32_32x32x16_bf16 v[32:47], v[164:167], v[116:119], v[32:47]
	v_mfma_f32_32x32x16_bf16 v[32:47], v[168:171], v[120:123], v[32:47]
	v_mfma_f32_32x32x16_bf16 v[32:47], v[172:175], v[124:127], v[32:47]
	s_waitcnt lgkmcnt(0)
	v_mfma_f32_32x32x16_bf16 v[16:31], v[224:227], v[112:115], v[16:31]
	v_mfma_f32_32x32x16_bf16 v[16:31], v[228:231], v[116:119], v[16:31]
	v_mfma_f32_32x32x16_bf16 v[16:31], v[232:235], v[120:123], v[16:31]
	v_mfma_f32_32x32x16_bf16 v[16:31], v[236:239], v[124:127], v[16:31]
.Ld_nopv_p0:
	s_cmp_lt_i32 s23, s24
	s_cbranch_scc1 .Ld_nosm_p0
	s_nop 7
	s_nop 7
	s_cmp_lg_u32 s23, s24
	s_cbranch_scc1 .Ld_notfirst_p0
	v_cmp_gt_i32_e64 s[46:47], 0, v205
	v_cmp_gt_i32_e64 s[48:49], 1, v205
	v_cmp_gt_i32_e64 s[50:51], 2, v205
	v_cmp_gt_i32_e64 s[52:53], 3, v205
	v_cndmask_b32_e64 v80, v80, v220, s[46:47]
	v_cmp_gt_i32_e64 s[46:47], 4, v205
	v_cndmask_b32_e64 v81, v81, v220, s[48:49]
	v_cmp_gt_i32_e64 s[48:49], 5, v205
	v_cndmask_b32_e64 v82, v82, v220, s[50:51]
	v_cmp_gt_i32_e64 s[50:51], 6, v205
	v_cndmask_b32_e64 v83, v83, v220, s[52:53]
	v_cmp_gt_i32_e64 s[52:53], 7, v205
	v_cndmask_b32_e64 v84, v84, v220, s[46:47]
	v_cmp_gt_i32_e64 s[46:47], 16, v205
	v_cndmask_b32_e64 v85, v85, v220, s[48:49]
	v_cmp_gt_i32_e64 s[48:49], 17, v205
	v_cndmask_b32_e64 v86, v86, v220, s[50:51]
	v_cmp_gt_i32_e64 s[50:51], 18, v205
	v_cndmask_b32_e64 v87, v87, v220, s[52:53]
	v_cmp_gt_i32_e64 s[52:53], 19, v205
	v_cndmask_b32_e64 v88, v88, v220, s[46:47]
	v_cmp_gt_i32_e64 s[46:47], 20, v205
	v_cndmask_b32_e64 v89, v89, v220, s[48:49]
	v_cmp_gt_i32_e64 s[48:49], 21, v205
	v_cndmask_b32_e64 v90, v90, v220, s[50:51]
	v_cmp_gt_i32_e64 s[50:51], 22, v205
	v_cndmask_b32_e64 v91, v91, v220, s[52:53]
	v_cmp_gt_i32_e64 s[52:53], 23, v205
	v_cndmask_b32_e64 v92, v92, v220, s[46:47]
	v_cmp_gt_i32_e64 s[46:47], 32, v205
	v_cndmask_b32_e64 v93, v93, v220, s[48:49]
	v_cmp_gt_i32_e64 s[48:49], 33, v205
	v_cndmask_b32_e64 v94, v94, v220, s[50:51]
	v_cmp_gt_i32_e64 s[50:51], 34, v205
	v_cndmask_b32_e64 v95, v95, v220, s[52:53]
	v_cmp_gt_i32_e64 s[52:53], 35, v205
	v_cndmask_b32_e64 v96, v96, v220, s[46:47]
	v_cmp_gt_i32_e64 s[46:47], 36, v205
	v_cndmask_b32_e64 v97, v97, v220, s[48:49]
	v_cmp_gt_i32_e64 s[48:49], 37, v205
	v_cndmask_b32_e64 v98, v98, v220, s[50:51]
	v_cmp_gt_i32_e64 s[50:51], 38, v205
	v_cndmask_b32_e64 v99, v99, v220, s[52:53]
	v_cmp_gt_i32_e64 s[52:53], 39, v205
	v_cndmask_b32_e64 v100, v100, v220, s[46:47]
	v_cmp_gt_i32_e64 s[46:47], 48, v205
	v_cndmask_b32_e64 v101, v101, v220, s[48:49]
	v_cmp_gt_i32_e64 s[48:49], 49, v205
	v_cndmask_b32_e64 v102, v102, v220, s[50:51]
	v_cmp_gt_i32_e64 s[50:51], 50, v205
	v_cndmask_b32_e64 v103, v103, v220, s[52:53]
	v_cmp_gt_i32_e64 s[52:53], 51, v205
	v_cndmask_b32_e64 v104, v104, v220, s[46:47]
	v_cmp_gt_i32_e64 s[46:47], 52, v205
	v_cndmask_b32_e64 v105, v105, v220, s[48:49]
	v_cmp_gt_i32_e64 s[48:49], 53, v205
	v_cndmask_b32_e64 v106, v106, v220, s[50:51]
	v_cmp_gt_i32_e64 s[50:51], 54, v205
	v_cndmask_b32_e64 v107, v107, v220, s[52:53]
	v_cmp_gt_i32_e64 s[52:53], 55, v205
	v_cndmask_b32_e64 v108, v108, v220, s[46:47]
	v_cndmask_b32_e64 v109, v109, v220, s[48:49]
	v_cndmask_b32_e64 v110, v110, v220, s[50:51]
	v_cndmask_b32_e64 v111, v111, v220, s[52:53]
	v_max3_f32 v246, v80, v81, v82
	v_max3_f32 v247, v96, v97, v98
	v_max3_f32 v246, v246, v83, v84
	v_max3_f32 v247, v247, v99, v100
	v_max3_f32 v246, v246, v85, v86
	v_max3_f32 v247, v247, v101, v102
	v_max3_f32 v246, v246, v87, v88
	v_max3_f32 v247, v247, v103, v104
	v_max3_f32 v246, v246, v89, v90
	v_max3_f32 v247, v247, v105, v106
	v_max3_f32 v246, v246, v91, v92
	v_max3_f32 v247, v247, v107, v108
	v_max3_f32 v246, v246, v93, v94
	v_max3_f32 v247, v247, v109, v110
	v_max3_f32 v246, v246, v95, v111
	v_max_f32_e32 v246, v246, v247
	s_nop 1
	ds_bpermute_b32 v247, v195, v246
	s_waitcnt lgkmcnt(0)
	v_max_f32_e32 v222, v246, v247
	v_sub_f32_e32 v80, v80, v222
	v_sub_f32_e32 v96, v96, v222
	v_sub_f32_e32 v81, v81, v222
	v_sub_f32_e32 v97, v97, v222
	v_sub_f32_e32 v82, v82, v222
	v_sub_f32_e32 v98, v98, v222
	v_sub_f32_e32 v83, v83, v222
	v_sub_f32_e32 v99, v99, v222
	v_sub_f32_e32 v84, v84, v222
	v_sub_f32_e32 v100, v100, v222
	v_sub_f32_e32 v85, v85, v222
	v_sub_f32_e32 v101, v101, v222
	v_sub_f32_e32 v86, v86, v222
	v_sub_f32_e32 v102, v102, v222
	v_sub_f32_e32 v87, v87, v222
	v_sub_f32_e32 v103, v103, v222
	v_sub_f32_e32 v88, v88, v222
	v_sub_f32_e32 v104, v104, v222
	v_sub_f32_e32 v89, v89, v222
	v_sub_f32_e32 v105, v105, v222
	v_sub_f32_e32 v90, v90, v222
	v_sub_f32_e32 v106, v106, v222
	v_sub_f32_e32 v91, v91, v222
	v_sub_f32_e32 v107, v107, v222
	v_sub_f32_e32 v92, v92, v222
	v_sub_f32_e32 v108, v108, v222
	v_sub_f32_e32 v93, v93, v222
	v_sub_f32_e32 v109, v109, v222
	v_sub_f32_e32 v94, v94, v222
	v_sub_f32_e32 v110, v110, v222
	v_sub_f32_e32 v95, v95, v222
	v_sub_f32_e32 v111, v111, v222
; template <int DQK, int DV, int FLAGS, int qp, int kp, int vts, int op> ...
;     ...
;             if (FLAGS & AF_ALIBI) { const float ab = -slope2 * (float)nrel - ((FLAGS & AF_ROBUST) ? 0.f : m);
; #pragma unroll
;                 for (int r = 0; r < 16; ++r) { const float c = (float)(16 * (r >> 3) + (r & 7)); p0[r] = __builtin_fmaf(slope2, c, ab); p1[r] = __builtin_fmaf(slope2, c + 32.f, ab); }
;             } else if (FLAGS & AF_ROBUST) {
; #pragma unroll
;                 for (int r = 0; r < 16; ++r) { p0[r] = 0.f; p1[r] = 0.f; }
;             } else { p0 = negm; p1 = negm; }
;             __builtin_amdgcn_sched_barrier(0);
; #pragma unroll
;             for (int c = 0; c < ND0 / 2; ++c) {
;                 if (c + 1 < ND0 / 2) {
; #pragma unroll
;                     for (int i = 0; i < 2; ++i) { kf[(c + 1) & 1][2 * i] = *(const LAS bf16x8*)(kb + (2 * c + 2 + i) * 32); kf[(c + 1) & 1][2 * i + 1] = *(const LAS bf16x8*)(kb + 32 * KROW + (2 * c + 2 + i) * 32); }
;                 }
; #pragma unroll
;                 for (int i = 0; i < 2; ++i) {
;                     p0 = __builtin_amdgcn_mfma_f32_32x32x16_bf16(kf[c & 1][2 * i], qr[2 * c + i], p0, 0, 0, 0);
;     ...
;             f32x2 rs2 = {0.f, 0.f};
; #pragma unroll
;             for (int r = 0; r < 16; ++r) { p0[r] = __builtin_amdgcn_exp2f(p0[r]); p1[r] = __builtin_amdgcn_exp2f(p1[r]); }
; #pragma unroll
;             for (int r = 0; r < 16; r += 2) { rs2 += (f32x2){p0[r], p0[r + 1]}; rs2 += (f32x2){p1[r], p1[r + 1]}; }
;             l += rs2.x + rs2.y;
;             bf16x8 pf[4];
;             pf[0] = pack_bf16x8(p0, 0); pf[1] = pack_bf16x8(p0, 8); pf[2] = pack_bf16x8(p1, 0); pf[3] = pack_bf16x8(p1, 8);
;             __builtin_amdgcn_sched_barrier(0);
; #pragma unroll
;             for (int d = 0; d < NDB; ++d) {
;                 if (d + 1 < NDB) {
; #pragma unroll
;                     for (int ks = 0; ks < 4; ++ks) vf[(d + 1) & 1][ks] = *(const LAS bf16x8*)(vb + (d + 1) * 32 * VROW + ks * 32);
;                 }
; #pragma unroll
;                 for (int ks = 0; ks < 4; ++ks) o[d] = __builtin_amdgcn_mfma_f32_32x32x16_bf16(vf[d & 1][ks], pf[ks], o[d], 0, 0, 0);
;                 __builtin_amdgcn_sched_barrier(0);
;             }
;         }
;         if (skip && more) ATT_GLOAD((FLAGS & AF_REV) ? t - 1 : t + 1);
;         if (more) ATT_LSTORE(cur ^ 1);
;         __syncthreads();
.Ld_notfirst_p0:
	v_exp_f32_e32 v80, v80
	v_exp_f32_e32 v81, v81
	v_exp_f32_e32 v96, v96
	v_exp_f32_e32 v97, v97
	v_pk_add_f32 v[240:241], v[80:81], 0 op_sel_hi:[1,0]
	v_exp_f32_e32 v82, v82
	v_exp_f32_e32 v83, v83
	v_pk_add_f32 v[240:241], v[96:97], v[240:241]
	v_exp_f32_e32 v98, v98
	v_exp_f32_e32 v99, v99
	v_pk_add_f32 v[240:241], v[82:83], v[240:241]
	v_exp_f32_e32 v84, v84
	v_exp_f32_e32 v85, v85
	v_pk_add_f32 v[240:241], v[98:99], v[240:241]
	v_exp_f32_e32 v100, v100
	v_exp_f32_e32 v101, v101
	v_pk_add_f32 v[240:241], v[84:85], v[240:241]
	v_exp_f32_e32 v86, v86
	v_exp_f32_e32 v87, v87
	v_pk_add_f32 v[240:241], v[100:101], v[240:241]
	v_exp_f32_e32 v102, v102
	v_exp_f32_e32 v103, v103
	v_pk_add_f32 v[240:241], v[86:87], v[240:241]
	v_exp_f32_e32 v88, v88
	v_exp_f32_e32 v89, v89
	v_pk_add_f32 v[240:241], v[102:103], v[240:241]
	v_exp_f32_e32 v104, v104
	v_exp_f32_e32 v105, v105
	v_pk_add_f32 v[240:241], v[88:89], v[240:241]
	v_exp_f32_e32 v90, v90
	v_exp_f32_e32 v91, v91
	v_pk_add_f32 v[240:241], v[104:105], v[240:241]
	v_exp_f32_e32 v106, v106
	v_exp_f32_e32 v107, v107
	v_pk_add_f32 v[240:241], v[90:91], v[240:241]
	v_exp_f32_e32 v92, v92
	v_exp_f32_e32 v93, v93
	v_pk_add_f32 v[240:241], v[106:107], v[240:241]
	v_exp_f32_e32 v108, v108
	v_exp_f32_e32 v109, v109
	v_pk_add_f32 v[240:241], v[92:93], v[240:241]
	v_exp_f32_e32 v94, v94
	v_exp_f32_e32 v95, v95
	v_pk_add_f32 v[240:241], v[108:109], v[240:241]
	v_exp_f32_e32 v110, v110
	v_exp_f32_e32 v111, v111
	v_pk_add_f32 v[240:241], v[94:95], v[240:241]
	s_nop 0
	v_pk_add_f32 v[240:241], v[110:111], v[240:241]
	v_cvt_pk_bf16_f32 v80, v80, v81
	v_cvt_pk_bf16_f32 v81, v82, v83
	v_cvt_pk_bf16_f32 v82, v84, v85
	v_cvt_pk_bf16_f32 v83, v86, v87
	v_cvt_pk_bf16_f32 v84, v88, v89
	v_cvt_pk_bf16_f32 v85, v90, v91
	v_cvt_pk_bf16_f32 v86, v92, v93
	v_cvt_pk_bf16_f32 v87, v94, v95
	v_cvt_pk_bf16_f32 v88, v96, v97
	v_cvt_pk_bf16_f32 v89, v98, v99
	v_cvt_pk_bf16_f32 v90, v100, v101
	v_cvt_pk_bf16_f32 v91, v102, v103
	v_cvt_pk_bf16_f32 v92, v104, v105
	v_cvt_pk_bf16_f32 v93, v106, v107
	v_cvt_pk_bf16_f32 v94, v108, v109
	v_cvt_pk_bf16_f32 v95, v110, v111
	v_add_f32_e32 v247, v240, v241
	v_add_f32_e32 v199, v199, v247
.Ld_nosm_p0:
	s_add_i32 s13, s23, 1
	s_cmp_ge_i32 s13, s3
	s_cbranch_scc1 .Ld_noqk_p0
	s_cmp_lt_i32 s13, s24
	s_cbranch_scc1 .Ld_noqk_p0
	s_add_i32 s12, s23, 1
	s_and_b32 s12, s12, 3
	s_mulk_i32 s12, 0x6c00
	v_add3_u32 v244, s12, v201, v194
	ds_read_b128 v[160:163], v244 offset:0
	ds_read_b128 v[164:167], v244 offset:32
	ds_read_b128 v[168:171], v244 offset:64
	ds_read_b128 v[172:175], v244 offset:96
	ds_read_b128 v[224:227], v244 offset:4608
	ds_read_b128 v[228:231], v244 offset:4640
	ds_read_b128 v[232:235], v244 offset:4672
	ds_read_b128 v[236:239], v244 offset:4704
	v_add_u32_e32 v246, 64, v205
	v_cvt_f32_i32_e32 v246, v246
	v_fma_f32 v242, -v14, v246, -v222
	v_mov_b32_e32 v112, v242
	v_add_f32_e32 v113, v14, v242
	v_pk_fma_f32 v[114:115], v[208:209], s[62:63], v[242:243] op_sel_hi:[1,1,0]
	v_pk_fma_f32 v[116:117], v[208:209], s[64:65], v[242:243] op_sel_hi:[1,1,0]
	v_pk_fma_f32 v[118:119], v[208:209], s[66:67], v[242:243] op_sel_hi:[1,1,0]
	v_pk_fma_f32 v[120:121], v[208:209], s[68:69], v[242:243] op_sel_hi:[1,1,0]
	v_pk_fma_f32 v[122:123], v[208:209], s[70:71], v[242:243] op_sel_hi:[1,1,0]
	v_pk_fma_f32 v[124:125], v[208:209], s[72:73], v[242:243] op_sel_hi:[1,1,0]
	v_pk_fma_f32 v[126:127], v[208:209], s[76:77], v[242:243] op_sel_hi:[1,1,0]
	v_pk_fma_f32 v[128:129], v[208:209], s[8:9], v[242:243] op_sel_hi:[1,1,0]
	v_pk_fma_f32 v[130:131], v[208:209], s[96:97], v[242:243] op_sel_hi:[1,1,0]
	v_pk_fma_f32 v[132:133], v[208:209], s[94:95], v[242:243] op_sel_hi:[1,1,0]
	v_pk_fma_f32 v[134:135], v[208:209], s[92:93], v[242:243] op_sel_hi:[1,1,0]
	v_pk_fma_f32 v[136:137], v[208:209], s[90:91], v[242:243] op_sel_hi:[1,1,0]
	v_pk_fma_f32 v[138:139], v[208:209], s[88:89], v[242:243] op_sel_hi:[1,1,0]
	v_pk_fma_f32 v[140:141], v[208:209], s[86:87], v[242:243] op_sel_hi:[1,1,0]
	v_pk_fma_f32 v[142:143], v[208:209], s[78:79], v[242:243] op_sel_hi:[1,1,0]
	s_waitcnt lgkmcnt(0)
	v_mfma_f32_32x32x16_bf16 v[112:127], v[160:163], v[2:5], v[112:127]
	v_mfma_f32_32x32x16_bf16 v[128:143], v[224:227], v[2:5], v[128:143]
	v_mfma_f32_32x32x16_bf16 v[112:127], v[164:167], v[6:9], v[112:127]
	v_mfma_f32_32x32x16_bf16 v[128:143], v[228:231], v[6:9], v[128:143]
	v_mfma_f32_32x32x16_bf16 v[112:127], v[168:171], v[10:13], v[112:127]
	v_mfma_f32_32x32x16_bf16 v[128:143], v[232:235], v[10:13], v[128:143]
	v_mfma_f32_32x32x16_bf16 v[112:127], v[172:175], v[144:147], v[112:127]
	v_mfma_f32_32x32x16_bf16 v[128:143], v[236:239], v[144:147], v[128:143]
.Ld_noqk_p0:
	s_cmp_lt_i32 s23, s24
	s_cbranch_scc1 .Ld_nopre_p0
	s_and_b32 s12, s23, 3
	s_mulk_i32 s12, 0x6c00
	v_add3_u32 v251, s12, v203, v194
	ds_read_b128 v[160:163], v251 offset:9216
	ds_read_b128 v[164:167], v251 offset:9248
	ds_read_b128 v[168:171], v251 offset:9280
	ds_read_b128 v[172:175], v251 offset:9312
.Ld_nopre_p0:
.Ld_tail0:
	s_add_i32 s12, s23, 2
	s_cmp_ge_i32 s12, s3
	s_cbranch_scc1 .Ld_nols_p0
	s_and_b32 s13, s12, 3
	s_mulk_i32 s13, 0x6c00
	s_waitcnt vmcnt(0)
	v_add_u32_e32 v248, s13, v204
	v_add_u32_e32 v249, s13, v200
	v_add_u32_e32 v250, s13, v202
	ds_write_b128 v248, v[148:151]
	ds_write_b128 v249, v[152:155] offset:9216
	ds_write_b128 v250, v[156:159] offset:9216
	s_add_i32 s12, s23, 3
	s_cmp_ge_i32 s12, s3
	s_cbranch_scc1 .Ld_nols_p0
	s_ashr_i32 s35, s34, 31
	s_lshl_b64 s[6:7], s[34:35], 17
	s_lshl_b64 s[10:11], s[34:35], 7
	s_add_u32 s10, s18, s10
	s_addc_u32 s11, s19, s11
	v_lshl_add_u64 v[246:247], v[206:207], 0, s[6:7]
	global_load_dwordx4 v[148:151], v[246:247], off
	v_lshl_add_u64 v[246:247], s[10:11], 0, v[0:1]
	global_load_dwordx4 v[152:155], v[246:247], off
	v_lshl_add_u64 v[246:247], s[10:11], 0, v[196:197]
	global_load_dwordx4 v[156:159], v[246:247], off
	s_add_i32 s34, s34, -1
; template <int DQK, int DV, int FLAGS, int qp, int kp, int vts, int op> ...
;     ...
;             if (FLAGS & AF_ALIBI) { const float ab = -slope2 * (float)nrel - ((FLAGS & AF_ROBUST) ? 0.f : m);
; #pragma unroll
;                 for (int r = 0; r < 16; ++r) { const float c = (float)(16 * (r >> 3) + (r & 7)); p0[r] = __builtin_fmaf(slope2, c, ab); p1[r] = __builtin_fmaf(slope2, c + 32.f, ab); }
;             } else if (FLAGS & AF_ROBUST) {
; #pragma unroll
;                 for (int r = 0; r < 16; ++r) { p0[r] = 0.f; p1[r] = 0.f; }
;             } else { p0 = negm; p1 = negm; }
;             __builtin_amdgcn_sched_barrier(0);
; #pragma unroll
;             for (int c = 0; c < ND0 / 2; ++c) {
;                 if (c + 1 < ND0 / 2) {
; #pragma unroll
;                     for (int i = 0; i < 2; ++i) { kf[(c + 1) & 1][2 * i] = *(const LAS bf16x8*)(kb + (2 * c + 2 + i) * 32); kf[(c + 1) & 1][2 * i + 1] = *(const LAS bf16x8*)(kb + 32 * KROW + (2 * c + 2 + i) * 32); }
;                 }
; #pragma unroll
;                 for (int i = 0; i < 2; ++i) {
;                     p0 = __builtin_amdgcn_mfma_f32_32x32x16_bf16(kf[c & 1][2 * i], qr[2 * c + i], p0, 0, 0, 0);
;     ...
;             f32x2 rs2 = {0.f, 0.f};
; #pragma unroll
;             for (int r = 0; r < 16; ++r) { p0[r] = __builtin_amdgcn_exp2f(p0[r]); p1[r] = __builtin_amdgcn_exp2f(p1[r]); }
; #pragma unroll
;             for (int r = 0; r < 16; r += 2) { rs2 += (f32x2){p0[r], p0[r + 1]}; rs2 += (f32x2){p1[r], p1[r + 1]}; }
;             l += rs2.x + rs2.y;
;             bf16x8 pf[4];
;             pf[0] = pack_bf16x8(p0, 0); pf[1] = pack_bf16x8(p0, 8); pf[2] = pack_bf16x8(p1, 0); pf[3] = pack_bf16x8(p1, 8);
;             __builtin_amdgcn_sched_barrier(0);
; #pragma unroll
;             for (int d = 0; d < NDB; ++d) {
;                 if (d + 1 < NDB) {
; #pragma unroll
;                     for (int ks = 0; ks < 4; ++ks) vf[(d + 1) & 1][ks] = *(const LAS bf16x8*)(vb + (d + 1) * 32 * VROW + ks * 32);
;                 }
; #pragma unroll
;                 for (int ks = 0; ks < 4; ++ks) o[d] = __builtin_amdgcn_mfma_f32_32x32x16_bf16(vf[d & 1][ks], pf[ks], o[d], 0, 0, 0);
;                 __builtin_amdgcn_sched_barrier(0);
;             }
;         }
;         if (skip && more) ATT_GLOAD((FLAGS & AF_REV) ? t - 1 : t + 1);
;         if (more) ATT_LSTORE(cur ^ 1);
;         __syncthreads();
;     }
.Ld_nols_p0:
	v_add_u32_e32 v205, 64, v205
	s_add_i32 s23, s23, 1
	s_cmp_ge_i32 s23, s3
	s_cbranch_scc1 .Ld_flush1
	s_waitcnt lgkmcnt(0)
	s_barrier
.Ld_top1:
	s_cmp_le_i32 s23, s24
	s_cbranch_scc1 .Ld_gen1
	s_add_i32 s13, s23, 1
	s_cmp_ge_i32 s13, s3
	s_cbranch_scc1 .Ld_gen1
	s_add_i32 s12, s23, -1
	s_and_b32 s12, s12, 3
	s_mulk_i32 s12, 0x6c00
	v_add3_u32 v245, s12, v203, v194
	ds_read_b128 v[224:227], v245 offset:13824
	ds_read_b128 v[228:231], v245 offset:13856
	ds_read_b128 v[232:235], v245 offset:13888
	ds_read_b128 v[236:239], v245 offset:13920
	s_add_i32 s12, s23, 1
	s_and_b32 s12, s12, 3
	s_mulk_i32 s12, 0x6c00
	v_add3_u32 v244, s12, v201, v194
	s_and_b32 s12, s23, 3
	s_mulk_i32 s12, 0x6c00
	v_add3_u32 v251, s12, v203, v194
	v_mfma_f32_32x32x16_bf16 v[64:79], v[160:163], v[80:83], v[64:79]
	v_mfma_f32_32x32x16_bf16 v[64:79], v[164:167], v[84:87], v[64:79]
	v_mfma_f32_32x32x16_bf16 v[64:79], v[168:171], v[88:91], v[64:79]
	v_mfma_f32_32x32x16_bf16 v[64:79], v[172:175], v[92:95], v[64:79]
	ds_read_b128 v[160:163], v245 offset:18432
	ds_read_b128 v[164:167], v245 offset:18464
	ds_read_b128 v[168:171], v245 offset:18496
	ds_read_b128 v[172:175], v245 offset:18528
	v_exp_f32_e32 v112, v112
	v_exp_f32_e32 v113, v113
	v_exp_f32_e32 v128, v128
	v_exp_f32_e32 v129, v129
	v_pk_add_f32 v[240:241], v[112:113], 0 op_sel_hi:[1,0]
	v_exp_f32_e32 v114, v114
	v_exp_f32_e32 v115, v115
	v_pk_add_f32 v[240:241], v[128:129], v[240:241]
	v_exp_f32_e32 v130, v130
	v_exp_f32_e32 v131, v131
	v_pk_add_f32 v[240:241], v[114:115], v[240:241]
	s_waitcnt lgkmcnt(4)
	v_mfma_f32_32x32x16_bf16 v[48:63], v[224:227], v[80:83], v[48:63]
	v_mfma_f32_32x32x16_bf16 v[48:63], v[228:231], v[84:87], v[48:63]
	v_mfma_f32_32x32x16_bf16 v[48:63], v[232:235], v[88:91], v[48:63]
	v_mfma_f32_32x32x16_bf16 v[48:63], v[236:239], v[92:95], v[48:63]
	ds_read_b128 v[224:227], v245 offset:23040
	ds_read_b128 v[228:231], v245 offset:23072
	ds_read_b128 v[232:235], v245 offset:23104
	ds_read_b128 v[236:239], v245 offset:23136
	v_exp_f32_e32 v116, v116
	v_exp_f32_e32 v117, v117
	v_pk_add_f32 v[240:241], v[130:131], v[240:241]
	v_exp_f32_e32 v132, v132
	v_exp_f32_e32 v133, v133
	v_pk_add_f32 v[240:241], v[116:117], v[240:241]
	v_exp_f32_e32 v118, v118
	v_exp_f32_e32 v119, v119
	v_pk_add_f32 v[240:241], v[132:133], v[240:241]
	v_exp_f32_e32 v134, v134
	v_exp_f32_e32 v135, v135
	v_pk_add_f32 v[240:241], v[118:119], v[240:241]
	s_waitcnt lgkmcnt(4)
	v_mfma_f32_32x32x16_bf16 v[32:47], v[160:163], v[80:83], v[32:47]
	v_mfma_f32_32x32x16_bf16 v[32:47], v[164:167], v[84:87], v[32:47]
	v_mfma_f32_32x32x16_bf16 v[32:47], v[168:171], v[88:91], v[32:47]
	v_mfma_f32_32x32x16_bf16 v[32:47], v[172:175], v[92:95], v[32:47]
	ds_read_b128 v[160:163], v244 offset:0
	ds_read_b128 v[164:167], v244 offset:32
	ds_read_b128 v[168:171], v244 offset:64
	ds_read_b128 v[172:175], v244 offset:96
	v_exp_f32_e32 v120, v120
	v_exp_f32_e32 v121, v121
	v_pk_add_f32 v[240:241], v[134:135], v[240:241]
	v_exp_f32_e32 v136, v136
	v_exp_f32_e32 v137, v137
	v_pk_add_f32 v[240:241], v[120:121], v[240:241]
	v_exp_f32_e32 v122, v122
	v_exp_f32_e32 v123, v123
	v_pk_add_f32 v[240:241], v[136:137], v[240:241]
	v_exp_f32_e32 v138, v138
	v_exp_f32_e32 v139, v139
	v_pk_add_f32 v[240:241], v[122:123], v[240:241]
	s_waitcnt lgkmcnt(4)
	v_mfma_f32_32x32x16_bf16 v[16:31], v[224:227], v[80:83], v[16:31]
	v_mfma_f32_32x32x16_bf16 v[16:31], v[228:231], v[84:87], v[16:31]
	v_mfma_f32_32x32x16_bf16 v[16:31], v[232:235], v[88:91], v[16:31]
	v_mfma_f32_32x32x16_bf16 v[16:31], v[236:239], v[92:95], v[16:31]
	ds_read_b128 v[224:227], v244 offset:4608
	ds_read_b128 v[228:231], v244 offset:4640
	ds_read_b128 v[232:235], v244 offset:4672
	ds_read_b128 v[236:239], v244 offset:4704
	v_add_u32_e32 v246, 64, v205
	v_cvt_f32_i32_e32 v246, v246
	v_fma_f32 v242, -v14, v246, -v222
	v_mov_b32_e32 v80, v242
	v_add_f32_e32 v81, v14, v242
	v_pk_fma_f32 v[82:83], v[208:209], s[62:63], v[242:243] op_sel_hi:[1,1,0]
	v_pk_fma_f32 v[84:85], v[208:209], s[64:65], v[242:243] op_sel_hi:[1,1,0]
	v_pk_fma_f32 v[86:87], v[208:209], s[66:67], v[242:243] op_sel_hi:[1,1,0]
	v_pk_fma_f32 v[88:89], v[208:209], s[68:69], v[242:243] op_sel_hi:[1,1,0]
	v_pk_fma_f32 v[90:91], v[208:209], s[70:71], v[242:243] op_sel_hi:[1,1,0]
	v_pk_fma_f32 v[92:93], v[208:209], s[72:73], v[242:243] op_sel_hi:[1,1,0]
	v_pk_fma_f32 v[94:95], v[208:209], s[76:77], v[242:243] op_sel_hi:[1,1,0]
	v_pk_fma_f32 v[96:97], v[208:209], s[8:9], v[242:243] op_sel_hi:[1,1,0]
	v_pk_fma_f32 v[98:99], v[208:209], s[96:97], v[242:243] op_sel_hi:[1,1,0]
	v_pk_fma_f32 v[100:101], v[208:209], s[94:95], v[242:243] op_sel_hi:[1,1,0]
	v_pk_fma_f32 v[102:103], v[208:209], s[92:93], v[242:243] op_sel_hi:[1,1,0]
	v_pk_fma_f32 v[104:105], v[208:209], s[90:91], v[242:243] op_sel_hi:[1,1,0]
	v_pk_fma_f32 v[106:107], v[208:209], s[88:89], v[242:243] op_sel_hi:[1,1,0]
	v_pk_fma_f32 v[108:109], v[208:209], s[86:87], v[242:243] op_sel_hi:[1,1,0]
	v_pk_fma_f32 v[110:111], v[208:209], s[78:79], v[242:243] op_sel_hi:[1,1,0]
	v_exp_f32_e32 v124, v124
	v_exp_f32_e32 v125, v125
	v_pk_add_f32 v[240:241], v[138:139], v[240:241]
	v_exp_f32_e32 v140, v140
	v_exp_f32_e32 v141, v141
	v_pk_add_f32 v[240:241], v[124:125], v[240:241]
	v_exp_f32_e32 v126, v126
	v_exp_f32_e32 v127, v127
	v_pk_add_f32 v[240:241], v[140:141], v[240:241]
	v_exp_f32_e32 v142, v142
	v_exp_f32_e32 v143, v143
	v_pk_add_f32 v[240:241], v[126:127], v[240:241]
	s_waitcnt lgkmcnt(4)
	v_mfma_f32_32x32x16_bf16 v[80:95], v[160:163], v[2:5], v[80:95]
	v_mfma_f32_32x32x16_bf16 v[80:95], v[164:167], v[6:9], v[80:95]
	v_mfma_f32_32x32x16_bf16 v[80:95], v[168:171], v[10:13], v[80:95]
	v_mfma_f32_32x32x16_bf16 v[80:95], v[172:175], v[144:147], v[80:95]
	ds_read_b128 v[160:163], v251 offset:9216
	ds_read_b128 v[164:167], v251 offset:9248
	ds_read_b128 v[168:171], v251 offset:9280
	ds_read_b128 v[172:175], v251 offset:9312
	s_nop 0
	v_pk_add_f32 v[240:241], v[142:143], v[240:241]
	v_cvt_pk_bf16_f32 v112, v112, v113
	v_cvt_pk_bf16_f32 v113, v114, v115
	v_cvt_pk_bf16_f32 v114, v116, v117
	v_cvt_pk_bf16_f32 v115, v118, v119
	v_cvt_pk_bf16_f32 v116, v120, v121
	v_cvt_pk_bf16_f32 v117, v122, v123
	v_cvt_pk_bf16_f32 v118, v124, v125
	v_cvt_pk_bf16_f32 v119, v126, v127
	s_waitcnt lgkmcnt(4)
	v_mfma_f32_32x32x16_bf16 v[96:111], v[224:227], v[2:5], v[96:111]
	v_mfma_f32_32x32x16_bf16 v[96:111], v[228:231], v[6:9], v[96:111]
	v_mfma_f32_32x32x16_bf16 v[96:111], v[232:235], v[10:13], v[96:111]
	v_mfma_f32_32x32x16_bf16 v[96:111], v[236:239], v[144:147], v[96:111]
	v_cvt_pk_bf16_f32 v120, v128, v129
	v_cvt_pk_bf16_f32 v121, v130, v131
	v_cvt_pk_bf16_f32 v122, v132, v133
	v_cvt_pk_bf16_f32 v123, v134, v135
	v_cvt_pk_bf16_f32 v124, v136, v137
	v_cvt_pk_bf16_f32 v125, v138, v139
	v_cvt_pk_bf16_f32 v126, v140, v141
	v_cvt_pk_bf16_f32 v127, v142, v143
	v_add_f32_e32 v247, v240, v241
	v_add_f32_e32 v199, v199, v247
	s_branch .Ld_tail1
; template <int DQK, int DV, int FLAGS, int qp, int kp, int vts, int op> ...
;     ...
;             bool need_mask = false;
;             if (FLAGS & AF_CAUSAL) need_mask = need_mask || (kv0 + 63 > qmin_w);
;             if (FLAGS & AF_WINDOW) need_mask = need_mask || (kv0 < qmax_w - (SWA_W - 1));
;             if (need_mask) {
; #pragma unroll
;                 for (int r = 0; r < 16; ++r) { const int c = 16 * (r >> 3) + (r & 7);
;                     bool m0 = false, m1 = false;
;                     if (FLAGS & AF_CAUSAL) { m0 = m0 || (c > nrel); m1 = m1 || (c + 32 > nrel); }
;                     if (FLAGS & AF_WINDOW) { m0 = m0 || (c <= nrel - SWA_W); m1 = m1 || (c + 32 <= nrel - SWA_W); }
;                     if (m0) p0[r] = -INFINITY; if (m1) p1[r] = -INFINITY; }
;             }
;             float mx = 0.f;
;             if ((FLAGS & AF_ROBUST) || !started || !skipmax) {
;               float a = MX3(p0[0], p0[1], p1[0]), b = MX3(p0[2], p0[3], p1[1]); a = MX3(a, p1[2], p1[3]);
; #pragma unroll
;               for (int r = 4; r < 16; r += 4) { a = MX3(a, p0[r], p0[r + 1]); b = MX3(b, p0[r + 2], p0[r + 3]); a = MX3(a, p1[r], p1[r + 1]); b = MX3(b, p1[r + 2], p1[r + 3]); }
;               mx = __builtin_fmaxf(a, b);
;               if ((FLAGS & AF_ROBUST) || !started) mx = __builtin_fmaxf(mx, shfl_xor_l(mx, 32, lane)); }
;             if (FLAGS & AF_ROBUST) {
;                 if (__any(mx > m + 8.0f)) {
;                     const float mn = fmaxf(m, mx), alpha = __builtin_amdgcn_exp2f(m - mn);
;                     l *= alpha; m = mn;
; #pragma unroll
;                     for (int d = 0; d < NDB; ++d)
; #pragma unroll
;                         for (int r = 0; r < 16; ++r) o[d][r] *= alpha;
;                 }
; #pragma unroll
;                 for (int r = 0; r < 16; ++r) { p0[r] -= m; p1[r] -= m; }
;             } else {
;                 if (!started) {
;                     started = true;
;                     m = mx;
; #pragma unroll
;                     for (int r = 0; r < 16; ++r) { p0[r] -= mx; p1[r] -= mx; }
;                     if (!(FLAGS & AF_ALIBI)) {
; #pragma unroll
;                         for (int r = 0; r < 16; ++r) negm[r] = -m;
;                     }
;     ...
;             __builtin_amdgcn_sched_barrier(0);
; #pragma unroll
;             for (int d = 0; d < NDB; ++d) {
;                 if (d + 1 < NDB) {
; #pragma unroll
.Ld_gen1:
	s_cmp_le_i32 s23, s24
	s_cbranch_scc1 .Ld_nopv_p1
	s_waitcnt lgkmcnt(0)
	s_add_i32 s12, s23, -1
	s_and_b32 s12, s12, 3
	s_mulk_i32 s12, 0x6c00
	v_add3_u32 v245, s12, v203, v194
	ds_read_b128 v[224:227], v245 offset:13824
	ds_read_b128 v[228:231], v245 offset:13856
	ds_read_b128 v[232:235], v245 offset:13888
	ds_read_b128 v[236:239], v245 offset:13920
	v_mfma_f32_32x32x16_bf16 v[64:79], v[160:163], v[80:83], v[64:79]
	v_mfma_f32_32x32x16_bf16 v[64:79], v[164:167], v[84:87], v[64:79]
	v_mfma_f32_32x32x16_bf16 v[64:79], v[168:171], v[88:91], v[64:79]
	v_mfma_f32_32x32x16_bf16 v[64:79], v[172:175], v[92:95], v[64:79]
	ds_read_b128 v[160:163], v245 offset:18432
	ds_read_b128 v[164:167], v245 offset:18464
	ds_read_b128 v[168:171], v245 offset:18496
	ds_read_b128 v[172:175], v245 offset:18528
	s_waitcnt lgkmcnt(4)
	v_mfma_f32_32x32x16_bf16 v[48:63], v[224:227], v[80:83], v[48:63]
	v_mfma_f32_32x32x16_bf16 v[48:63], v[228:231], v[84:87], v[48:63]
	v_mfma_f32_32x32x16_bf16 v[48:63], v[232:235], v[88:91], v[48:63]
	v_mfma_f32_32x32x16_bf16 v[48:63], v[236:239], v[92:95], v[48:63]
	ds_read_b128 v[224:227], v245 offset:23040
	ds_read_b128 v[228:231], v245 offset:23072
	ds_read_b128 v[232:235], v245 offset:23104
	ds_read_b128 v[236:239], v245 offset:23136
	s_waitcnt lgkmcnt(4)
	v_mfma_f32_32x32x16_bf16 v[32:47], v[160:163], v[80:83], v[32:47]
	v_mfma_f32_32x32x16_bf16 v[32:47], v[164:167], v[84:87], v[32:47]
	v_mfma_f32_32x32x16_bf16 v[32:47], v[168:171], v[88:91], v[32:47]
	v_mfma_f32_32x32x16_bf16 v[32:47], v[172:175], v[92:95], v[32:47]
	s_waitcnt lgkmcnt(0)
	v_mfma_f32_32x32x16_bf16 v[16:31], v[224:227], v[80:83], v[16:31]
	v_mfma_f32_32x32x16_bf16 v[16:31], v[228:231], v[84:87], v[16:31]
	v_mfma_f32_32x32x16_bf16 v[16:31], v[232:235], v[88:91], v[16:31]
	v_mfma_f32_32x32x16_bf16 v[16:31], v[236:239], v[92:95], v[16:31]
.Ld_nopv_p1:
	s_cmp_lt_i32 s23, s24
	s_cbranch_scc1 .Ld_nosm_p1
	s_nop 7
	s_nop 7
	s_cmp_lg_u32 s23, s24
	s_cbranch_scc1 .Ld_notfirst_p1
	v_cmp_gt_i32_e64 s[46:47], 0, v205
	v_cmp_gt_i32_e64 s[48:49], 1, v205
	v_cmp_gt_i32_e64 s[50:51], 2, v205
	v_cmp_gt_i32_e64 s[52:53], 3, v205
	v_cndmask_b32_e64 v112, v112, v220, s[46:47]
	v_cmp_gt_i32_e64 s[46:47], 4, v205
	v_cndmask_b32_e64 v113, v113, v220, s[48:49]
	v_cmp_gt_i32_e64 s[48:49], 5, v205
	v_cndmask_b32_e64 v114, v114, v220, s[50:51]
	v_cmp_gt_i32_e64 s[50:51], 6, v205
	v_cndmask_b32_e64 v115, v115, v220, s[52:53]
	v_cmp_gt_i32_e64 s[52:53], 7, v205
	v_cndmask_b32_e64 v116, v116, v220, s[46:47]
	v_cmp_gt_i32_e64 s[46:47], 16, v205
	v_cndmask_b32_e64 v117, v117, v220, s[48:49]
	v_cmp_gt_i32_e64 s[48:49], 17, v205
	v_cndmask_b32_e64 v118, v118, v220, s[50:51]
	v_cmp_gt_i32_e64 s[50:51], 18, v205
	v_cndmask_b32_e64 v119, v119, v220, s[52:53]
	v_cmp_gt_i32_e64 s[52:53], 19, v205
	v_cndmask_b32_e64 v120, v120, v220, s[46:47]
	v_cmp_gt_i32_e64 s[46:47], 20, v205
	v_cndmask_b32_e64 v121, v121, v220, s[48:49]
	v_cmp_gt_i32_e64 s[48:49], 21, v205
	v_cndmask_b32_e64 v122, v122, v220, s[50:51]
	v_cmp_gt_i32_e64 s[50:51], 22, v205
	v_cndmask_b32_e64 v123, v123, v220, s[52:53]
	v_cmp_gt_i32_e64 s[52:53], 23, v205
	v_cndmask_b32_e64 v124, v124, v220, s[46:47]
	v_cmp_gt_i32_e64 s[46:47], 32, v205
	v_cndmask_b32_e64 v125, v125, v220, s[48:49]
	v_cmp_gt_i32_e64 s[48:49], 33, v205
	v_cndmask_b32_e64 v126, v126, v220, s[50:51]
	v_cmp_gt_i32_e64 s[50:51], 34, v205
	v_cndmask_b32_e64 v127, v127, v220, s[52:53]
	v_cmp_gt_i32_e64 s[52:53], 35, v205
	v_cndmask_b32_e64 v128, v128, v220, s[46:47]
	v_cmp_gt_i32_e64 s[46:47], 36, v205
	v_cndmask_b32_e64 v129, v129, v220, s[48:49]
	v_cmp_gt_i32_e64 s[48:49], 37, v205
	v_cndmask_b32_e64 v130, v130, v220, s[50:51]
	v_cmp_gt_i32_e64 s[50:51], 38, v205
	v_cndmask_b32_e64 v131, v131, v220, s[52:53]
	v_cmp_gt_i32_e64 s[52:53], 39, v205
	v_cndmask_b32_e64 v132, v132, v220, s[46:47]
	v_cmp_gt_i32_e64 s[46:47], 48, v205
	v_cndmask_b32_e64 v133, v133, v220, s[48:49]
	v_cmp_gt_i32_e64 s[48:49], 49, v205
	v_cndmask_b32_e64 v134, v134, v220, s[50:51]
	v_cmp_gt_i32_e64 s[50:51], 50, v205
	v_cndmask_b32_e64 v135, v135, v220, s[52:53]
	v_cmp_gt_i32_e64 s[52:53], 51, v205
	v_cndmask_b32_e64 v136, v136, v220, s[46:47]
	v_cmp_gt_i32_e64 s[46:47], 52, v205
	v_cndmask_b32_e64 v137, v137, v220, s[48:49]
	v_cmp_gt_i32_e64 s[48:49], 53, v205
	v_cndmask_b32_e64 v138, v138, v220, s[50:51]
	v_cmp_gt_i32_e64 s[50:51], 54, v205
	v_cndmask_b32_e64 v139, v139, v220, s[52:53]
	v_cmp_gt_i32_e64 s[52:53], 55, v205
	v_cndmask_b32_e64 v140, v140, v220, s[46:47]
	v_cndmask_b32_e64 v141, v141, v220, s[48:49]
	v_cndmask_b32_e64 v142, v142, v220, s[50:51]
	v_cndmask_b32_e64 v143, v143, v220, s[52:53]
	v_max3_f32 v246, v112, v113, v114
	v_max3_f32 v247, v128, v129, v130
	v_max3_f32 v246, v246, v115, v116
	v_max3_f32 v247, v247, v131, v132
	v_max3_f32 v246, v246, v117, v118
	v_max3_f32 v247, v247, v133, v134
	v_max3_f32 v246, v246, v119, v120
	v_max3_f32 v247, v247, v135, v136
	v_max3_f32 v246, v246, v121, v122
	v_max3_f32 v247, v247, v137, v138
	v_max3_f32 v246, v246, v123, v124
	v_max3_f32 v247, v247, v139, v140
	v_max3_f32 v246, v246, v125, v126
	v_max3_f32 v247, v247, v141, v142
	v_max3_f32 v246, v246, v127, v143
	v_max_f32_e32 v246, v246, v247
	s_nop 1
	ds_bpermute_b32 v247, v195, v246
	s_waitcnt lgkmcnt(0)
	v_max_f32_e32 v222, v246, v247
	v_sub_f32_e32 v112, v112, v222
	v_sub_f32_e32 v128, v128, v222
	v_sub_f32_e32 v113, v113, v222
	v_sub_f32_e32 v129, v129, v222
	v_sub_f32_e32 v114, v114, v222
	v_sub_f32_e32 v130, v130, v222
	v_sub_f32_e32 v115, v115, v222
	v_sub_f32_e32 v131, v131, v222
	v_sub_f32_e32 v116, v116, v222
	v_sub_f32_e32 v132, v132, v222
	v_sub_f32_e32 v117, v117, v222
	v_sub_f32_e32 v133, v133, v222
	v_sub_f32_e32 v118, v118, v222
	v_sub_f32_e32 v134, v134, v222
	v_sub_f32_e32 v119, v119, v222
	v_sub_f32_e32 v135, v135, v222
	v_sub_f32_e32 v120, v120, v222
	v_sub_f32_e32 v136, v136, v222
	v_sub_f32_e32 v121, v121, v222
	v_sub_f32_e32 v137, v137, v222
	v_sub_f32_e32 v122, v122, v222
	v_sub_f32_e32 v138, v138, v222
	v_sub_f32_e32 v123, v123, v222
	v_sub_f32_e32 v139, v139, v222
	v_sub_f32_e32 v124, v124, v222
	v_sub_f32_e32 v140, v140, v222
	v_sub_f32_e32 v125, v125, v222
	v_sub_f32_e32 v141, v141, v222
	v_sub_f32_e32 v126, v126, v222
	v_sub_f32_e32 v142, v142, v222
	v_sub_f32_e32 v127, v127, v222
	v_sub_f32_e32 v143, v143, v222
; #define LAS __attribute__((address_space(3)))
; template <int DQK, int DV, int FLAGS, int qp, int kp, int vts, int op> ...
;     ...
;             if (FLAGS & AF_ALIBI) { const float ab = -slope2 * (float)nrel - ((FLAGS & AF_ROBUST) ? 0.f : m);
; #pragma unroll
;                 for (int r = 0; r < 16; ++r) { const float c = (float)(16 * (r >> 3) + (r & 7)); p0[r] = __builtin_fmaf(slope2, c, ab); p1[r] = __builtin_fmaf(slope2, c + 32.f, ab); }
;             } else if (FLAGS & AF_ROBUST) {
; #pragma unroll
;                 for (int r = 0; r < 16; ++r) { p0[r] = 0.f; p1[r] = 0.f; }
;             } else { p0 = negm; p1 = negm; }
;             __builtin_amdgcn_sched_barrier(0);
; #pragma unroll
;             for (int c = 0; c < ND0 / 2; ++c) {
;                 if (c + 1 < ND0 / 2) {
; #pragma unroll
;                     for (int i = 0; i < 2; ++i) { kf[(c + 1) & 1][2 * i] = *(const LAS bf16x8*)(kb + (2 * c + 2 + i) * 32); kf[(c + 1) & 1][2 * i + 1] = *(const LAS bf16x8*)(kb + 32 * KROW + (2 * c + 2 + i) * 32); }
;                 }
; #pragma unroll
;                 for (int i = 0; i < 2; ++i) {
;                     p0 = __builtin_amdgcn_mfma_f32_32x32x16_bf16(kf[c & 1][2 * i], qr[2 * c + i], p0, 0, 0, 0);
;                     p1 = __builtin_amdgcn_mfma_f32_32x32x16_bf16(kf[c & 1][2 * i + 1], qr[2 * c + i], p1, 0, 0, 0);
;                 }
;                 __builtin_amdgcn_sched_barrier(0);
;             }
;     ...
;             f32x2 rs2 = {0.f, 0.f};
; #pragma unroll
;             for (int r = 0; r < 16; ++r) { p0[r] = __builtin_amdgcn_exp2f(p0[r]); p1[r] = __builtin_amdgcn_exp2f(p1[r]); }
; #pragma unroll
;             for (int r = 0; r < 16; r += 2) { rs2 += (f32x2){p0[r], p0[r + 1]}; rs2 += (f32x2){p1[r], p1[r + 1]}; }
;             l += rs2.x + rs2.y;
;             bf16x8 pf[4];
;             pf[0] = pack_bf16x8(p0, 0); pf[1] = pack_bf16x8(p0, 8); pf[2] = pack_bf16x8(p1, 0); pf[3] = pack_bf16x8(p1, 8);
.Ld_notfirst_p1:
	v_exp_f32_e32 v112, v112
	v_exp_f32_e32 v113, v113
	v_exp_f32_e32 v128, v128
	v_exp_f32_e32 v129, v129
	v_pk_add_f32 v[240:241], v[112:113], 0 op_sel_hi:[1,0]
	v_exp_f32_e32 v114, v114
	v_exp_f32_e32 v115, v115
	v_pk_add_f32 v[240:241], v[128:129], v[240:241]
	v_exp_f32_e32 v130, v130
	v_exp_f32_e32 v131, v131
	v_pk_add_f32 v[240:241], v[114:115], v[240:241]
	v_exp_f32_e32 v116, v116
	v_exp_f32_e32 v117, v117
	v_pk_add_f32 v[240:241], v[130:131], v[240:241]
	v_exp_f32_e32 v132, v132
	v_exp_f32_e32 v133, v133
	v_pk_add_f32 v[240:241], v[116:117], v[240:241]
	v_exp_f32_e32 v118, v118
	v_exp_f32_e32 v119, v119
	v_pk_add_f32 v[240:241], v[132:133], v[240:241]
	v_exp_f32_e32 v134, v134
	v_exp_f32_e32 v135, v135
	v_pk_add_f32 v[240:241], v[118:119], v[240:241]
	v_exp_f32_e32 v120, v120
	v_exp_f32_e32 v121, v121
	v_pk_add_f32 v[240:241], v[134:135], v[240:241]
	v_exp_f32_e32 v136, v136
	v_exp_f32_e32 v137, v137
	v_pk_add_f32 v[240:241], v[120:121], v[240:241]
	v_exp_f32_e32 v122, v122
	v_exp_f32_e32 v123, v123
	v_pk_add_f32 v[240:241], v[136:137], v[240:241]
	v_exp_f32_e32 v138, v138
	v_exp_f32_e32 v139, v139
	v_pk_add_f32 v[240:241], v[122:123], v[240:241]
	v_exp_f32_e32 v124, v124
	v_exp_f32_e32 v125, v125
	v_pk_add_f32 v[240:241], v[138:139], v[240:241]
	v_exp_f32_e32 v140, v140
	v_exp_f32_e32 v141, v141
	v_pk_add_f32 v[240:241], v[124:125], v[240:241]
	v_exp_f32_e32 v126, v126
	v_exp_f32_e32 v127, v127
	v_pk_add_f32 v[240:241], v[140:141], v[240:241]
	v_exp_f32_e32 v142, v142
	v_exp_f32_e32 v143, v143
	v_pk_add_f32 v[240:241], v[126:127], v[240:241]
	s_nop 0
	v_pk_add_f32 v[240:241], v[142:143], v[240:241]
	v_cvt_pk_bf16_f32 v112, v112, v113
	v_cvt_pk_bf16_f32 v113, v114, v115
	v_cvt_pk_bf16_f32 v114, v116, v117
	v_cvt_pk_bf16_f32 v115, v118, v119
	v_cvt_pk_bf16_f32 v116, v120, v121
	v_cvt_pk_bf16_f32 v117, v122, v123
	v_cvt_pk_bf16_f32 v118, v124, v125
	v_cvt_pk_bf16_f32 v119, v126, v127
	v_cvt_pk_bf16_f32 v120, v128, v129
	v_cvt_pk_bf16_f32 v121, v130, v131
	v_cvt_pk_bf16_f32 v122, v132, v133
	v_cvt_pk_bf16_f32 v123, v134, v135
	v_cvt_pk_bf16_f32 v124, v136, v137
	v_cvt_pk_bf16_f32 v125, v138, v139
	v_cvt_pk_bf16_f32 v126, v140, v141
	v_cvt_pk_bf16_f32 v127, v142, v143
	v_add_f32_e32 v247, v240, v241
	v_add_f32_e32 v199, v199, v247
.Ld_nosm_p1:
	s_add_i32 s13, s23, 1
	s_cmp_ge_i32 s13, s3
	s_cbranch_scc1 .Ld_noqk_p1
	s_cmp_lt_i32 s13, s24
	s_cbranch_scc1 .Ld_noqk_p1
	s_add_i32 s12, s23, 1
	s_and_b32 s12, s12, 3
	s_mulk_i32 s12, 0x6c00
	v_add3_u32 v244, s12, v201, v194
	ds_read_b128 v[160:163], v244 offset:0
	ds_read_b128 v[164:167], v244 offset:32
	ds_read_b128 v[168:171], v244 offset:64
	ds_read_b128 v[172:175], v244 offset:96
	ds_read_b128 v[224:227], v244 offset:4608
	ds_read_b128 v[228:231], v244 offset:4640
	ds_read_b128 v[232:235], v244 offset:4672
	ds_read_b128 v[236:239], v244 offset:4704
	v_add_u32_e32 v246, 64, v205
	v_cvt_f32_i32_e32 v246, v246
	v_fma_f32 v242, -v14, v246, -v222
	v_mov_b32_e32 v80, v242
	v_add_f32_e32 v81, v14, v242
	v_pk_fma_f32 v[82:83], v[208:209], s[62:63], v[242:243] op_sel_hi:[1,1,0]
	v_pk_fma_f32 v[84:85], v[208:209], s[64:65], v[242:243] op_sel_hi:[1,1,0]
	v_pk_fma_f32 v[86:87], v[208:209], s[66:67], v[242:243] op_sel_hi:[1,1,0]
	v_pk_fma_f32 v[88:89], v[208:209], s[68:69], v[242:243] op_sel_hi:[1,1,0]
	v_pk_fma_f32 v[90:91], v[208:209], s[70:71], v[242:243] op_sel_hi:[1,1,0]
	v_pk_fma_f32 v[92:93], v[208:209], s[72:73], v[242:243] op_sel_hi:[1,1,0]
	v_pk_fma_f32 v[94:95], v[208:209], s[76:77], v[242:243] op_sel_hi:[1,1,0]
	v_pk_fma_f32 v[96:97], v[208:209], s[8:9], v[242:243] op_sel_hi:[1,1,0]
	v_pk_fma_f32 v[98:99], v[208:209], s[96:97], v[242:243] op_sel_hi:[1,1,0]
	v_pk_fma_f32 v[100:101], v[208:209], s[94:95], v[242:243] op_sel_hi:[1,1,0]
	v_pk_fma_f32 v[102:103], v[208:209], s[92:93], v[242:243] op_sel_hi:[1,1,0]
	v_pk_fma_f32 v[104:105], v[208:209], s[90:91], v[242:243] op_sel_hi:[1,1,0]
	v_pk_fma_f32 v[106:107], v[208:209], s[88:89], v[242:243] op_sel_hi:[1,1,0]
	v_pk_fma_f32 v[108:109], v[208:209], s[86:87], v[242:243] op_sel_hi:[1,1,0]
	v_pk_fma_f32 v[110:111], v[208:209], s[78:79], v[242:243] op_sel_hi:[1,1,0]
	s_waitcnt lgkmcnt(0)
	v_mfma_f32_32x32x16_bf16 v[80:95], v[160:163], v[2:5], v[80:95]
	v_mfma_f32_32x32x16_bf16 v[96:111], v[224:227], v[2:5], v[96:111]
	v_mfma_f32_32x32x16_bf16 v[80:95], v[164:167], v[6:9], v[80:95]
	v_mfma_f32_32x32x16_bf16 v[96:111], v[228:231], v[6:9], v[96:111]
	v_mfma_f32_32x32x16_bf16 v[80:95], v[168:171], v[10:13], v[80:95]
	v_mfma_f32_32x32x16_bf16 v[96:111], v[232:235], v[10:13], v[96:111]
	v_mfma_f32_32x32x16_bf16 v[80:95], v[172:175], v[144:147], v[80:95]
	v_mfma_f32_32x32x16_bf16 v[96:111], v[236:239], v[144:147], v[96:111]

; #define LAS __attribute__((address_space(3)))
; #define ATT_LSTORE(buf) do { LAS unsigned char* b_ = lds + (buf) * BUF; \
;         _Pragma("unroll") for (int i = 0; i < KPT; ++i) { if (KCH % NTHREADS == 0 || tid + i * NTHREADS < KCH) *(LAS u32x4*)(b_ + klo[i]) = kreg[i]; } \
;         _Pragma("unroll") for (int i = 0; i < VPT; ++i) *(LAS u32x4*)(b_ + vlo[i]) = vreg[i]; } while (0)
; template <int DQK, int DV, int FLAGS, int qp, int kp, int vts, int op> ...
;     ...
;             __builtin_amdgcn_sched_barrier(0);
; #pragma unroll
;             for (int d = 0; d < NDB; ++d) {
;                 if (d + 1 < NDB) {
; #pragma unroll
;                     for (int ks = 0; ks < 4; ++ks) vf[(d + 1) & 1][ks] = *(const LAS bf16x8*)(vb + (d + 1) * 32 * VROW + ks * 32);
;                 }
; #pragma unroll
;                 for (int ks = 0; ks < 4; ++ks) o[d] = __builtin_amdgcn_mfma_f32_32x32x16_bf16(vf[d & 1][ks], pf[ks], o[d], 0, 0, 0);
;                 __builtin_amdgcn_sched_barrier(0);
;             }
;         }
;         if (skip && more) ATT_GLOAD((FLAGS & AF_REV) ? t - 1 : t + 1);
;         if (more) ATT_LSTORE(cur ^ 1);
;         __syncthreads();
;     }
.Ld_nols_p1:
	v_add_u32_e32 v205, 64, v205
	s_add_i32 s23, s23, 1
	s_cmp_ge_i32 s23, s3
	s_cbranch_scc1 .Ld_flush0
	s_waitcnt lgkmcnt(0)
	s_barrier
	s_branch .Ld_top0
.Ld_flush0:
	s_waitcnt lgkmcnt(0)
	s_add_i32 s12, s23, -1
	s_and_b32 s12, s12, 3
	s_mulk_i32 s12, 0x6c00
	v_add3_u32 v245, s12, v203, v194
	ds_read_b128 v[224:227], v245 offset:13824
	ds_read_b128 v[228:231], v245 offset:13856
	ds_read_b128 v[232:235], v245 offset:13888
	ds_read_b128 v[236:239], v245 offset:13920
	v_mfma_f32_32x32x16_bf16 v[64:79], v[160:163], v[112:115], v[64:79]
	v_mfma_f32_32x32x16_bf16 v[64:79], v[164:167], v[116:119], v[64:79]
	v_mfma_f32_32x32x16_bf16 v[64:79], v[168:171], v[120:123], v[64:79]
	v_mfma_f32_32x32x16_bf16 v[64:79], v[172:175], v[124:127], v[64:79]
	ds_read_b128 v[160:163], v245 offset:18432
	ds_read_b128 v[164:167], v245 offset:18464
	ds_read_b128 v[168:171], v245 offset:18496
	ds_read_b128 v[172:175], v245 offset:18528
	s_waitcnt lgkmcnt(4)
	v_mfma_f32_32x32x16_bf16 v[48:63], v[224:227], v[112:115], v[48:63]
	v_mfma_f32_32x32x16_bf16 v[48:63], v[228:231], v[116:119], v[48:63]
	v_mfma_f32_32x32x16_bf16 v[48:63], v[232:235], v[120:123], v[48:63]
	v_mfma_f32_32x32x16_bf16 v[48:63], v[236:239], v[124:127], v[48:63]
	ds_read_b128 v[224:227], v245 offset:23040
	ds_read_b128 v[228:231], v245 offset:23072
	ds_read_b128 v[232:235], v245 offset:23104
	ds_read_b128 v[236:239], v245 offset:23136
	s_waitcnt lgkmcnt(4)
	v_mfma_f32_32x32x16_bf16 v[32:47], v[160:163], v[112:115], v[32:47]
	v_mfma_f32_32x32x16_bf16 v[32:47], v[164:167], v[116:119], v[32:47]
	v_mfma_f32_32x32x16_bf16 v[32:47], v[168:171], v[120:123], v[32:47]
	v_mfma_f32_32x32x16_bf16 v[32:47], v[172:175], v[124:127], v[32:47]
	s_waitcnt lgkmcnt(0)
	v_mfma_f32_32x32x16_bf16 v[16:31], v[224:227], v[112:115], v[16:31]
	v_mfma_f32_32x32x16_bf16 v[16:31], v[228:231], v[116:119], v[16:31]
	v_mfma_f32_32x32x16_bf16 v[16:31], v[232:235], v[120:123], v[16:31]
	v_mfma_f32_32x32x16_bf16 v[16:31], v[236:239], v[124:127], v[16:31]
	s_branch .LBB0_957
.Ld_flush1:
	s_waitcnt lgkmcnt(0)
	s_add_i32 s12, s23, -1
	s_and_b32 s12, s12, 3
	s_mulk_i32 s12, 0x6c00
	v_add3_u32 v245, s12, v203, v194
	ds_read_b128 v[224:227], v245 offset:13824
	ds_read_b128 v[228:231], v245 offset:13856
	ds_read_b128 v[232:235], v245 offset:13888
	ds_read_b128 v[236:239], v245 offset:13920
	v_mfma_f32_32x32x16_bf16 v[64:79], v[160:163], v[80:83], v[64:79]
	v_mfma_f32_32x32x16_bf16 v[64:79], v[164:167], v[84:87], v[64:79]
	v_mfma_f32_32x32x16_bf16 v[64:79], v[168:171], v[88:91], v[64:79]
	v_mfma_f32_32x32x16_bf16 v[64:79], v[172:175], v[92:95], v[64:79]
	ds_read_b128 v[160:163], v245 offset:18432
	ds_read_b128 v[164:167], v245 offset:18464
	ds_read_b128 v[168:171], v245 offset:18496
	ds_read_b128 v[172:175], v245 offset:18528
	s_waitcnt lgkmcnt(4)
	v_mfma_f32_32x32x16_bf16 v[48:63], v[224:227], v[80:83], v[48:63]
	v_mfma_f32_32x32x16_bf16 v[48:63], v[228:231], v[84:87], v[48:63]
	v_mfma_f32_32x32x16_bf16 v[48:63], v[232:235], v[88:91], v[48:63]
	v_mfma_f32_32x32x16_bf16 v[48:63], v[236:239], v[92:95], v[48:63]
	ds_read_b128 v[224:227], v245 offset:23040
	ds_read_b128 v[228:231], v245 offset:23072
	ds_read_b128 v[232:235], v245 offset:23104
	ds_read_b128 v[236:239], v245 offset:23136
	s_waitcnt lgkmcnt(4)
	v_mfma_f32_32x32x16_bf16 v[32:47], v[160:163], v[80:83], v[32:47]
	v_mfma_f32_32x32x16_bf16 v[32:47], v[164:167], v[84:87], v[32:47]
	v_mfma_f32_32x32x16_bf16 v[32:47], v[168:171], v[88:91], v[32:47]
	v_mfma_f32_32x32x16_bf16 v[32:47], v[172:175], v[92:95], v[32:47]
	s_waitcnt lgkmcnt(0)
	v_mfma_f32_32x32x16_bf16 v[16:31], v[224:227], v[80:83], v[16:31]
	v_mfma_f32_32x32x16_bf16 v[16:31], v[228:231], v[84:87], v[16:31]
	v_mfma_f32_32x32x16_bf16 v[16:31], v[232:235], v[88:91], v[16:31]
	v_mfma_f32_32x32x16_bf16 v[16:31], v[236:239], v[92:95], v[16:31]
	s_branch .LBB0_957
.Ld_fallback:
	s_branch .LBB0_936
.LBB0_935:
	s_add_i32 s23, s23, 1
	s_add_i32 s34, s34, -1
	s_sub_i32 s22, s22, 64
	s_cmp_lg_u32 s3, s23
	v_add_u32_e32 v205, 64, v205
	s_waitcnt lgkmcnt(0)
	s_barrier
	s_cbranch_scc0 .LBB0_957
